# grid barrier: non-leader workgroups poll the top-level generation word directly
# speedup vs baseline: 1.0190x; 1.0001x over previous
.LBB0_84:
	s_or_b64 exec, exec, s[14:15]
	v_cvt_f32_u32_e32 v1, v4
	s_waitcnt vmcnt(0)
	v_readfirstlane_b32 s3, v5
	v_sub_u32_e32 v5, 0, v4
	v_rcp_iflag_f32_e32 v1, v1
	v_add_u32_e32 v6, s3, v3
	v_mul_f32_e32 v1, 0x4f7ffffe, v1
	v_cvt_u32_f32_e32 v1, v1
	v_mul_lo_u32 v3, v5, v1
	v_mul_hi_u32 v3, v1, v3
	v_add_u32_e32 v1, v1, v3
	v_mul_hi_u32 v1, v6, v1
	v_mul_lo_u32 v3, v1, v4
	v_sub_u32_e32 v3, v6, v3
	v_add_u32_e32 v5, 1, v1
	v_cmp_ge_u32_e32 vcc, v3, v4
	s_nop 1
	v_cndmask_b32_e32 v1, v1, v5, vcc
	v_sub_u32_e32 v5, v3, v4
	v_cndmask_b32_e32 v3, v3, v5, vcc
	v_add_u32_e32 v5, 1, v1
	v_cmp_ge_u32_e32 vcc, v3, v4
	s_nop 1
	v_cndmask_b32_e32 v3, v1, v5, vcc
	v_mul_lo_u32 v5, v4, v3
	v_add_u32_e32 v1, 1, v6
	v_add_u32_e32 v4, v5, v4
	v_cmp_ne_u32_e32 vcc, v1, v4
	s_and_saveexec_b64 s[6:7], vcc
	s_xor_b64 s[12:13], exec, s[6:7]
	s_cbranch_execz .LBB0_98
	v_mov_b32_e32 v1, 0
	s_add_u32 s18, s88, 0x4500
	s_addc_u32 s19, s89, 0
	global_load_dword v1, v1, s[18:19] sc1
	s_waitcnt vmcnt(0)
	v_cmp_eq_u32_e32 vcc, v1, v3
	s_and_saveexec_b64 s[14:15], vcc
	s_cbranch_execz .LBB0_97
	s_add_u32 s16, s88, 0x1200
	s_addc_u32 s17, s89, 0
	s_mov_b32 s3, 1
	s_mov_b64 s[20:21], 0
	s_waitcnt lgkmcnt(0)
	v_mov_b32_e32 v2, 0
	s_branch .LBB0_88

.LBB0_166:
	s_or_b64 exec, exec, s[12:13]
	v_cvt_f32_u32_e32 v1, v4
	s_waitcnt vmcnt(0)
	v_readfirstlane_b32 s3, v5
	v_sub_u32_e32 v5, 0, v4
	v_rcp_iflag_f32_e32 v1, v1
	v_add_u32_e32 v6, s3, v3
	v_mul_f32_e32 v1, 0x4f7ffffe, v1
	v_cvt_u32_f32_e32 v1, v1
	v_mul_lo_u32 v3, v5, v1
	v_mul_hi_u32 v3, v1, v3
	v_add_u32_e32 v1, v1, v3
	v_mul_hi_u32 v1, v6, v1
	v_mul_lo_u32 v3, v1, v4
	v_sub_u32_e32 v3, v6, v3
	v_add_u32_e32 v5, 1, v1
	v_cmp_ge_u32_e32 vcc, v3, v4
	s_nop 1
	v_cndmask_b32_e32 v1, v1, v5, vcc
	v_sub_u32_e32 v5, v3, v4
	v_cndmask_b32_e32 v3, v3, v5, vcc
	v_add_u32_e32 v5, 1, v1
	v_cmp_ge_u32_e32 vcc, v3, v4
	s_nop 1
	v_cndmask_b32_e32 v3, v1, v5, vcc
	v_mul_lo_u32 v5, v4, v3
	v_add_u32_e32 v1, 1, v6
	v_add_u32_e32 v4, v5, v4
	v_cmp_ne_u32_e32 vcc, v1, v4
	s_and_saveexec_b64 s[6:7], vcc
	s_xor_b64 s[10:11], exec, s[6:7]
	s_cbranch_execz .LBB0_180
	v_mov_b32_e32 v1, 0
	s_add_u32 s16, s88, 0x4500
	s_addc_u32 s17, s89, 0
	global_load_dword v1, v1, s[16:17] sc1
	s_waitcnt vmcnt(0)
	v_cmp_eq_u32_e32 vcc, v1, v3
	s_and_saveexec_b64 s[12:13], vcc
	s_cbranch_execz .LBB0_179
	s_add_u32 s14, s88, 0x1200
	s_addc_u32 s15, s89, 0
	s_mov_b32 s3, 1
	s_mov_b64 s[18:19], 0
	s_waitcnt lgkmcnt(0)
	v_mov_b32_e32 v2, 0
	s_branch .LBB0_170

.LBB0_1385:
	s_or_b64 exec, exec, s[12:13]
	v_cvt_f32_u32_e32 v4, v2
	s_waitcnt vmcnt(0)
	v_readfirstlane_b32 s3, v3
	v_sub_u32_e32 v3, 0, v2
	v_rcp_iflag_f32_e32 v4, v4
	v_add_u32_e32 v5, s3, v1
	v_mul_f32_e32 v4, 0x4f7ffffe, v4
	v_cvt_u32_f32_e32 v4, v4
	v_mul_lo_u32 v1, v3, v4
	v_mul_hi_u32 v1, v4, v1
	v_add_u32_e32 v1, v4, v1
	v_mul_hi_u32 v1, v5, v1
	v_mul_lo_u32 v3, v1, v2
	v_sub_u32_e32 v3, v5, v3
	v_add_u32_e32 v4, 1, v1
	v_cmp_ge_u32_e32 vcc, v3, v2
	s_nop 1
	v_cndmask_b32_e32 v1, v1, v4, vcc
	v_sub_u32_e32 v4, v3, v2
	v_cndmask_b32_e32 v3, v3, v4, vcc
	v_add_u32_e32 v4, 1, v1
	v_cmp_ge_u32_e32 vcc, v3, v2
	v_add_u32_e32 v3, 1, v5
	s_nop 0
	v_cndmask_b32_e32 v1, v1, v4, vcc
	v_mul_lo_u32 v4, v2, v1
	v_add_u32_e32 v2, v4, v2
	v_cmp_ne_u32_e32 vcc, v3, v2
	s_and_saveexec_b64 s[8:9], vcc
	s_xor_b64 s[8:9], exec, s[8:9]
	s_cbranch_execz .LBB0_1399
	s_waitcnt lgkmcnt(0)
	v_mov_b32_e32 v0, 0
	s_add_u32 s16, s88, 0x4500
	s_addc_u32 s17, s89, 0
	global_load_dword v0, v0, s[16:17] sc1
	s_waitcnt vmcnt(0)
	v_cmp_eq_u32_e32 vcc, v0, v1
	s_and_saveexec_b64 s[12:13], vcc
	s_cbranch_execz .LBB0_1398
	s_add_u32 s14, s88, 0x1200
	s_addc_u32 s15, s89, 0
	s_mov_b32 s3, 1
	s_mov_b64 s[18:19], 0
	v_mov_b32_e32 v0, 0
	s_branch .LBB0_1389
